# mix phase static priority: filler items at s_setprio 3, diff-latent waves at 0
# speedup vs baseline: 1.0356x; 1.0076x over previous
.Lmix_dispatch:
	s_setprio 3
	s_cmpk_gt_i32 s40, 0xff
	s_cbranch_scc0 .LBB0_261
	s_cmpk_gt_u32 s40, 0x1ff
	s_cbranch_scc0 .LBB0_262
	s_cmpk_gt_u32 s40, 0x2ff
	s_cbranch_scc0 .LBB0_263
	s_cmpk_gt_u32 s40, 0x3ff
	s_cbranch_scc0 .LBB0_264
	s_cmpk_gt_u32 s40, 0x5ff
	s_cbranch_scc0 .LBB0_265
	s_cmpk_gt_u32 s40, 0x7ff
	s_cbranch_scc0 .LBB0_266
	s_cmpk_gt_u32 s40, 0x9ff
	s_cbranch_scc0 .LBB0_267
	s_cmpk_gt_u32 s40, 0xaff
	s_mov_b64 s[2:3], -1
	s_cbranch_scc0 .LBB0_268
	v_readlane_b32 s12, v252, 2
	v_readlane_b32 s72, v253, 51
	v_readlane_b32 s18, v252, 8
	v_readlane_b32 s20, v252, 10
	v_readlane_b32 s21, v252, 11
	v_readlane_b32 s76, v253, 55
	v_readlane_b32 s77, v253, 56
	s_lshl_b32 s6, s40, 2
	s_mov_b32 s7, -4
	v_readlane_b32 s16, v252, 6
	v_readlane_b32 s17, v252, 7
	s_mov_b64 s[20:21], s[76:77]
	s_movk_i32 s18, 0x104
	v_readlane_b32 s13, v252, 3
	v_readlane_b32 s14, v252, 4
	v_readlane_b32 s15, v252, 5
	v_readlane_b32 s19, v252, 9
	v_readlane_b32 s22, v252, 12
	v_readlane_b32 s23, v252, 13
	v_readlane_b32 s24, v252, 14
	v_readlane_b32 s25, v252, 15
	v_readlane_b32 s26, v252, 16
	v_readlane_b32 s27, v252, 17
	v_readlane_b32 s73, v253, 52
	v_readlane_b32 s74, v253, 53
	v_readlane_b32 s75, v253, 54
	v_readlane_b32 s78, v253, 57
	v_readlane_b32 s79, v253, 58
	v_readlane_b32 s80, v253, 59
	v_readlane_b32 s81, v253, 60
	v_readlane_b32 s82, v253, 61
	v_readlane_b32 s83, v253, 62
	v_readlane_b32 s84, v253, 63
	v_readlane_b32 s85, v254, 0
	v_readlane_b32 s86, v254, 1
	v_readlane_b32 s87, v254, 2
